# s15 + attention: p1 log2 fma and 7-11 of the 16 p0 exps write their final registers inside the P.V MFMA gaps 13..16 (registers released by the MFMAs), 16+16 VALU after the barrier reduced to 9/5 movs
# baseline (speedup 1.0000x reference)
; __device__ __forceinline__ void finishSM(f32x16& p0, f32x16& p1, float alpha, float& l_reg, bf16x8& pa0, bf16x8& pa1, bf16x8& pa2, bf16x8& pa3) {
;   for (int r = 0; r < 16; ++r) p1[r] = __builtin_amdgcn_exp2f(p1[r]);
;   float ps = 0; for (int r = 0; r < 16; ++r) ps += p0[r]; for (int r = 0; r < 16; ++r) ps += p1[r];
;   { auto rr = __builtin_amdgcn_permlane32_swap(__float_as_uint(ps), __float_as_uint(ps), false, false);
;     ps = __uint_as_float(rr[0]) + __uint_as_float(rr[1]); }
;   l_reg = l_reg * alpha + ps;
;     ...
;   PK4(p0, 0, pa0); PK4(p0, 8, pa1); PK4(p1, 0, pa2); PK4(p1, 8, pa3);
;     ...
; }
; __device__ __forceinline__ void qkt(f32x16& p0, f32x16& p1, const bf16* Ks, const bf16x8* qr, int r32, int hi) {
;   p0 = f32x16{}; p1 = f32x16{};
;   for (int d0 = 0; d0 < 8; ++d0) { int cb = (d0 * 16 + hi * 8) * 2;
;     bf16x8 b0 = *reinterpret_cast<const bf16x8*>((const char*)Ks + KSWZ(r32, cb));
;     bf16x8 b1 = *reinterpret_cast<const bf16x8*>((const char*)Ks + KSWZ(32 + r32, cb));
;     p0 = __builtin_amdgcn_mfma_f32_32x32x16_bf16(b0, qr[d0], p0, 0, 0, 0);
;     p1 = __builtin_amdgcn_mfma_f32_32x32x16_bf16(b1, qr[d0], p1, 0, 0, 0); }
.LBB0_602:
	ds_read_b128 v[64:67], v192 offset:49152
	ds_read_b128 v[68:71], v192 offset:57344
	ds_read_b128 v[242:245], v201 offset:49152
	ds_read_b128 v[246:249], v201 offset:57344
	v_exp_f32_e32 v160, v162
	v_add_f32_e32 v162, 0, v223
	s_waitcnt lgkmcnt(3)
	v_mfma_f32_32x32x16_bf16 v[80:95], v[64:67], v[126:129], 0
	v_add_f32_e32 v162, v224, v162
	v_add_f32_e32 v162, v225, v162
	v_add_f32_e32 v162, v227, v162
	v_add_f32_e32 v162, v229, v162
	v_add_f32_e32 v162, v230, v162
	v_add_f32_e32 v162, v226, v162
	v_add_f32_e32 v162, v228, v162
	s_waitcnt lgkmcnt(2)
	v_mfma_f32_32x32x16_bf16 v[64:79], v[68:71], v[126:129], 0
	v_add_f32_e32 v162, v215, v162
	v_add_f32_e32 v162, v217, v162
	v_add_f32_e32 v162, v219, v162
	v_add_f32_e32 v162, v221, v162
	v_add_f32_e32 v162, v216, v162
	v_add_f32_e32 v162, v218, v162
	v_add_f32_e32 v162, v220, v162
	s_waitcnt lgkmcnt(1)
	v_mfma_f32_32x32x16_bf16 v[80:95], v[242:245], v[122:125], v[80:95]
	v_add_f32_e32 v162, v222, v162
	v_exp_f32_e32 v154, v164
	v_exp_f32_e32 v155, v165
	v_exp_f32_e32 v156, v172
	v_exp_f32_e32 v157, v173
	v_exp_f32_e32 v158, v168
	v_exp_f32_e32 v159, v169
	s_waitcnt lgkmcnt(0)
	v_mfma_f32_32x32x16_bf16 v[64:79], v[246:249], v[122:125], v[64:79]
	ds_read_b128 v[242:245], v200 offset:49152
	ds_read_b128 v[246:249], v200 offset:57344
	v_exp_f32_e32 v161, v163
	v_cvt_pk_bf16_f32 v164, v229, v230
	v_cvt_pk_bf16_f32 v163, v225, v227
	v_cvt_pk_bf16_f32 v165, v226, v228
	v_cvt_pk_bf16_f32 v168, v216, v218
	v_cvt_pk_bf16_f32 v169, v220, v222
	s_waitcnt lgkmcnt(1)
	v_mfma_f32_32x32x16_bf16 v[80:95], v[242:245], v[134:137], v[80:95]
	v_exp_f32_e32 v146, v176
	v_exp_f32_e32 v147, v177
	v_exp_f32_e32 v148, v174
	v_exp_f32_e32 v149, v175
	v_permlane32_swap_b32_e32 v163, v165
	s_waitcnt lgkmcnt(0)
	v_mfma_f32_32x32x16_bf16 v[64:79], v[246:249], v[134:137], v[64:79]
	ds_read_b128 v[242:245], v195 offset:49152
	ds_read_b128 v[246:249], v195 offset:57344
	v_add_f32_e32 v162, v146, v162
	v_add_f32_e32 v162, v147, v162
	v_add_f32_e32 v162, v148, v162
	v_exp_f32_e32 v150, v170
	s_waitcnt lgkmcnt(1)
	v_mfma_f32_32x32x16_bf16 v[80:95], v[242:245], v[130:133], v[80:95]
	v_exp_f32_e32 v151, v171
	v_exp_f32_e32 v152, v166
	v_exp_f32_e32 v153, v167
	v_add_f32_e32 v162, v149, v162
	s_waitcnt lgkmcnt(0)
	v_mfma_f32_32x32x16_bf16 v[64:79], v[246:249], v[130:133], v[64:79]
	ds_read_b128 v[242:245], v194 offset:49152
	ds_read_b128 v[246:249], v194 offset:57344
	v_add_f32_e32 v162, v150, v162
	v_add_f32_e32 v162, v151, v162
	v_add_f32_e32 v162, v152, v162
	v_add_f32_e32 v162, v153, v162
	s_waitcnt lgkmcnt(1)
	v_mfma_f32_32x32x16_bf16 v[80:95], v[242:245], v[118:121], v[80:95]
	v_add_f32_e32 v162, v154, v162
	v_add_f32_e32 v162, v155, v162
	v_add_f32_e32 v162, v156, v162
	v_add_f32_e32 v162, v157, v162
	s_waitcnt lgkmcnt(0)
	v_mfma_f32_32x32x16_bf16 v[64:79], v[246:249], v[118:121], v[64:79]
	ds_read_b128 v[242:245], v193 offset:49152
	ds_read_b128 v[246:249], v193 offset:57344
	v_add_f32_e32 v162, v158, v162
	v_add_f32_e32 v162, v159, v162
	v_add_f32_e32 v162, v160, v162
	v_add_f32_e32 v211, v161, v162
	s_waitcnt lgkmcnt(1)
	v_mfma_f32_32x32x16_bf16 v[80:95], v[242:245], v[114:117], v[80:95]
	v_mov_b32_e32 v212, v211
	v_cvt_pk_bf16_f32 v162, v223, v224
	s_nop 0
	v_permlane32_swap_b32_e32 v211, v212
	s_waitcnt lgkmcnt(0)
	v_mfma_f32_32x32x16_bf16 v[64:79], v[246:249], v[114:117], v[64:79]
	ds_read_b128 v[242:245], v207 offset:49152
	ds_read_b128 v[246:249], v207 offset:57344
	v_permlane32_swap_b32_e32 v162, v164
	v_cvt_pk_bf16_f32 v166, v215, v217
	v_cvt_pk_bf16_f32 v167, v219, v221
	v_cvt_pk_bf16_f32 v170, v146, v147
	s_waitcnt lgkmcnt(1)
	v_mfma_f32_32x32x16_bf16 v[80:95], v[242:245], v[110:113], v[80:95]
	v_cvt_pk_bf16_f32 v171, v148, v149
	v_cvt_pk_bf16_f32 v172, v150, v151
	v_cvt_pk_bf16_f32 v173, v152, v153
	v_cvt_pk_bf16_f32 v174, v154, v155
	s_waitcnt lgkmcnt(0)
	v_mfma_f32_32x32x16_bf16 v[64:79], v[246:249], v[110:113], v[64:79]
	ds_read_b128 v[242:245], v206 offset:49152
	ds_read_b128 v[246:249], v206 offset:57344
	v_cvt_pk_bf16_f32 v175, v156, v157
	v_cvt_pk_bf16_f32 v176, v158, v159
	v_cvt_pk_bf16_f32 v177, v160, v161
	s_waitcnt lgkmcnt(1)
	v_mfma_f32_32x32x16_bf16 v[80:95], v[242:245], v[106:109], v[80:95]
	v_permlane32_swap_b32_e32 v166, v168
	v_permlane32_swap_b32_e32 v167, v169
	v_permlane32_swap_b32_e32 v170, v172
	s_waitcnt lgkmcnt(0)
	v_mfma_f32_32x32x16_bf16 v[64:79], v[246:249], v[106:109], v[64:79]
	v_permlane32_swap_b32_e32 v171, v173
	v_permlane32_swap_b32_e32 v174, v176
	v_permlane32_swap_b32_e32 v175, v177
	v_add_co_u32_e32 v146, vcc, s69, v182
	s_mov_b32 s8, 0xffff0000
	s_nop 0
	v_addc_co_u32_e32 v147, vcc, -1, v183, vcc
	v_add_co_u32_e32 v150, vcc, s8, v182
	s_mov_b32 s8, 0xff6e8000
	s_nop 0
	v_addc_co_u32_e32 v151, vcc, -1, v183, vcc
	v_add_co_u32_e32 v154, vcc, s8, v182
	s_mov_b32 s8, 0xff6f0000
	s_nop 0
	v_addc_co_u32_e32 v155, vcc, -1, v183, vcc
	v_add_co_u32_e32 v158, vcc, s8, v182
	global_load_dwordx4 v[146:149], v[146:147], off
	s_nop 0
	global_load_dwordx4 v[150:153], v[150:151], off
	v_addc_co_u32_e32 v159, vcc, -1, v183, vcc
	global_load_dwordx4 v[154:157], v[154:155], off
	s_nop 0
	global_load_dwordx4 v[158:161], v[158:159], off
	ds_read_b64_tr_b16 v[214:215], v179 offset:0
	ds_read_b64_tr_b16 v[216:217], v179 offset:0x800
	ds_read_b64_tr_b16 v[218:219], v179 offset:0x1000
	ds_read_b64_tr_b16 v[220:221], v179 offset:0x1800
	ds_read_b64_tr_b16 v[222:223], v179 offset:0x2000
	ds_read_b64_tr_b16 v[224:225], v179 offset:0x2800
	ds_read_b64_tr_b16 v[226:227], v179 offset:0x3000
	ds_read_b64_tr_b16 v[228:229], v179 offset:0x3800
	s_waitcnt vmcnt(4)
; #define SBAR() __builtin_amdgcn_sched_barrier(0)
; __device__ __forceinline__ void partialSM(f32x16& p0, f32x16& p1, float& m_reg, float& mn, float& alpha) {
;   constexpr float C = SCALE * 1.4426950408889634f;
;   float pmax = p0[0]; for (int r = 1; r < 16; ++r) pmax = fmaxf(pmax, p0[r]); for (int r = 0; r < 16; ++r) pmax = fmaxf(pmax, p1[r]);
;   { auto rr = __builtin_amdgcn_permlane32_swap(__float_as_uint(pmax), __float_as_uint(pmax), false, false);
;     pmax = fmaxf(__uint_as_float(rr[0]), __uint_as_float(rr[1])); }
;   if (__builtin_expect(__all(pmax - m_reg <= THR / SCALE), 1)) { mn = m_reg; alpha = 1.f; }
;   else { mn = fmaxf(m_reg, pmax); alpha = __builtin_amdgcn_exp2f((m_reg - mn) * C); m_reg = mn; }
;   float mnC = -mn * C;
;   for (int r = 0; r < 16; ++r) p0[r] = fmaf(p0[r], C, mnC); for (int r = 0; r < 16; ++r) p1[r] = fmaf(p1[r], C, mnC);
;   for (int r = 0; r < 16; ++r) p0[r] = __builtin_amdgcn_exp2f(p0[r]);
; template <int D0> __device__ __forceinline__ void pv_one(f32x16& od, int vb, bf16x8 pa0, bf16x8 pa1, bf16x8 pa2, bf16x8 pa3) {
;   const s16x4 l0 = tr_read<v_rd_off(D0, 0, 0)>(vb), h0 = tr_read<v_rd_off(D0, 0, 1)>(vb), l1 = tr_read<v_rd_off(D0, 1, 0)>(vb), h1 = tr_read<v_rd_off(D0, 1, 1)>(vb);
;   const s16x4 l2 = tr_read<v_rd_off(D0, 2, 0)>(vb), h2 = tr_read<v_rd_off(D0, 2, 1)>(vb), l3 = tr_read<v_rd_off(D0, 3, 0)>(vb), h3 = tr_read<v_rd_off(D0, 3, 1)>(vb);
;   asm volatile("s_waitcnt lgkmcnt(0)" ::: "memory"); SBAR();
;     ...
;   od = __builtin_amdgcn_mfma_f32_32x32x16_bf16(pa0, PK(l0, h0), od, 0, 0, 0);
;   od = __builtin_amdgcn_mfma_f32_32x32x16_bf16(pa1, PK(l1, h1), od, 0, 0, 0);
;   od = __builtin_amdgcn_mfma_f32_32x32x16_bf16(pa2, PK(l2, h2), od, 0, 0, 0);
;   od = __builtin_amdgcn_mfma_f32_32x32x16_bf16(pa3, PK(l3, h3), od, 0, 0, 0);
;     ...
; }
; __device__ __forceinline__ void pv_d0(f32x16* o, int vb, bf16x8 pa0, bf16x8 pa1, bf16x8 pa2, bf16x8 pa3) {
;   pv_one<0>(o[0], vb, pa0, pa1, pa2, pa3); pv_one<1>(o[1], vb, pa0, pa1, pa2, pa3); pv_one<2>(o[2], vb, pa0, pa1, pa2, pa3); pv_one<3>(o[3], vb, pa0, pa1, pa2, pa3);
	ds_write_b128 v202, v[102:105] offset:32768
	ds_write_b128 v203, v[142:145] offset:32768
	s_waitcnt lgkmcnt(2)
	s_nop 0
	v_mfma_f32_32x32x16_bf16 v[0:15], v[162:165], v[214:217], v[0:15]
	ds_read_b64_tr_b16 v[214:215], v179 offset:0x200
	ds_read_b64_tr_b16 v[216:217], v179 offset:0xa00
	v_max_f32_e32 v232, v81, v81
	v_max_f32_e32 v233, v80, v80
	v_max_f32_e32 v232, v233, v232
	v_max3_f32 v232, v232, v82, v83
	v_max3_f32 v232, v232, v84, v85
	v_max3_f32 v232, v232, v86, v87
	v_mfma_f32_32x32x16_bf16 v[0:15], v[166:169], v[218:221], v[0:15]
	ds_read_b64_tr_b16 v[218:219], v179 offset:0x1200
	ds_read_b64_tr_b16 v[220:221], v179 offset:0x1a00
	v_max3_f32 v232, v232, v88, v89
	v_max3_f32 v232, v232, v90, v91
	v_max3_f32 v232, v232, v92, v93
	v_max3_f32 v232, v232, v94, v95
	v_max3_f32 v232, v232, v64, v65
	v_max3_f32 v232, v232, v66, v67
	v_mfma_f32_32x32x16_bf16 v[0:15], v[170:173], v[222:225], v[0:15]
	ds_read_b64_tr_b16 v[222:223], v179 offset:0x2200
	ds_read_b64_tr_b16 v[224:225], v179 offset:0x2a00
	v_max3_f32 v232, v232, v68, v69
	v_max3_f32 v232, v232, v70, v71
	v_max3_f32 v232, v232, v72, v73
	v_max3_f32 v232, v232, v74, v75
	v_max3_f32 v232, v232, v76, v77
	v_max3_f32 v232, v232, v78, v79
	v_mfma_f32_32x32x16_bf16 v[0:15], v[174:177], v[226:229], v[0:15]
	ds_read_b64_tr_b16 v[226:227], v179 offset:0x3200
	ds_read_b64_tr_b16 v[228:229], v179 offset:0x3a00
	v_mov_b32_e32 v233, v232
	s_nop 1
	v_permlane32_swap_b32_e32 v232, v233
	v_max_f32_e32 v233, v233, v233
	v_max_f32_e32 v232, v232, v232
	v_max_f32_e32 v232, v232, v233
	s_waitcnt lgkmcnt(0)
	v_mfma_f32_32x32x16_bf16 v[48:63], v[162:165], v[214:217], v[48:63]
	ds_read_b64_tr_b16 v[214:215], v179 offset:0x400
	ds_read_b64_tr_b16 v[216:217], v179 offset:0xc00
	v_sub_f32_e32 v233, v232, v210
	v_cmp_ge_f32_e32 vcc, s68, v233
	v_max_f32_e32 v233, v210, v210
	v_max_f32_e32 v232, v233, v232
	v_sub_f32_e32 v233, v210, v232
	v_mul_f32_e32 v233, 0x3e0293ee, v233
	v_mfma_f32_32x32x16_bf16 v[48:63], v[166:169], v[218:221], v[48:63]
	ds_read_b64_tr_b16 v[218:219], v179 offset:0x1400
	ds_read_b64_tr_b16 v[220:221], v179 offset:0x1c00
	s_cmp_eq_u64 vcc, exec
	s_cselect_b64 s[8:9], -1, 0
	v_exp_f32_e32 v233, v233
	v_mfma_f32_32x32x16_bf16 v[48:63], v[170:173], v[222:225], v[48:63]
	ds_read_b64_tr_b16 v[222:223], v179 offset:0x2400
	ds_read_b64_tr_b16 v[224:225], v179 offset:0x2c00
	v_cndmask_b32_e64 v210, v232, v210, s[8:9]
	v_mul_f32_e32 v213, 0xbe0293ee, v210
	v_fmamk_f32 v80, v80, 0x3e0293ee, v213
	v_fmamk_f32 v81, v81, 0x3e0293ee, v213
	v_fmamk_f32 v82, v82, 0x3e0293ee, v213
	v_fmamk_f32 v83, v83, 0x3e0293ee, v213
	v_mfma_f32_32x32x16_bf16 v[48:63], v[174:177], v[226:229], v[48:63]
	ds_read_b64_tr_b16 v[226:227], v179 offset:0x3400
	ds_read_b64_tr_b16 v[228:229], v179 offset:0x3c00
	v_fmamk_f32 v84, v84, 0x3e0293ee, v213
	v_fmamk_f32 v85, v85, 0x3e0293ee, v213
	v_fmamk_f32 v86, v86, 0x3e0293ee, v213
	v_fmamk_f32 v87, v87, 0x3e0293ee, v213
	v_exp_f32_e32 v83, v83
	s_waitcnt lgkmcnt(0)
	v_mfma_f32_32x32x16_bf16 v[32:47], v[162:165], v[214:217], v[32:47]
	ds_read_b64_tr_b16 v[214:215], v179 offset:0x600
	ds_read_b64_tr_b16 v[216:217], v179 offset:0xe00
	v_fmamk_f32 v88, v88, 0x3e0293ee, v213
	v_fmamk_f32 v89, v89, 0x3e0293ee, v213
	v_fmamk_f32 v90, v90, 0x3e0293ee, v213
	v_fmamk_f32 v91, v91, 0x3e0293ee, v213
	v_exp_f32_e32 v84, v84
	v_mfma_f32_32x32x16_bf16 v[32:47], v[166:169], v[218:221], v[32:47]
	ds_read_b64_tr_b16 v[218:219], v179 offset:0x1600
	ds_read_b64_tr_b16 v[220:221], v179 offset:0x1e00
	v_fmamk_f32 v92, v92, 0x3e0293ee, v213
	v_fmamk_f32 v93, v93, 0x3e0293ee, v213
	v_fmamk_f32 v94, v94, 0x3e0293ee, v213
	v_fmamk_f32 v95, v95, 0x3e0293ee, v213
	v_exp_f32_e32 v85, v85
	v_mfma_f32_32x32x16_bf16 v[32:47], v[170:173], v[222:225], v[32:47]
	ds_read_b64_tr_b16 v[222:223], v179 offset:0x2600
	ds_read_b64_tr_b16 v[224:225], v179 offset:0x2e00
	v_exp_f32_e32 v87, v87
	v_exp_f32_e32 v90, v90
	v_exp_f32_e32 v91, v91
	v_mfma_f32_32x32x16_bf16 v[32:47], v[174:177], v[226:229], v[32:47]
	ds_read_b64_tr_b16 v[226:227], v179 offset:0x3600
	ds_read_b64_tr_b16 v[228:229], v179 offset:0x3e00
	v_exp_f32_e32 v93, v93
	v_exp_f32_e32 v94, v94
	v_exp_f32_e32 v95, v95
	s_waitcnt lgkmcnt(0)
	v_mfma_f32_32x32x16_bf16 v[16:31], v[162:165], v[214:217], v[16:31]
	v_exp_f32_e32 v162, v80
	v_exp_f32_e32 v163, v81
	v_fmamk_f32 v216, v69, 0x3e0293ee, v213
	v_fmamk_f32 v217, v70, 0x3e0293ee, v213
	v_fmamk_f32 v215, v76, 0x3e0293ee, v213
	v_mfma_f32_32x32x16_bf16 v[16:31], v[166:169], v[218:221], v[16:31]
	v_exp_f32_e32 v164, v82
	v_exp_f32_e32 v165, v86
	v_fmamk_f32 v218, v71, 0x3e0293ee, v213
	v_fmamk_f32 v219, v72, 0x3e0293ee, v213
	v_fmamk_f32 v220, v73, 0x3e0293ee, v213
	v_fmamk_f32 v221, v74, 0x3e0293ee, v213
	v_mfma_f32_32x32x16_bf16 v[16:31], v[170:173], v[222:225], v[16:31]
	v_exp_f32_e32 v166, v88
	v_exp_f32_e32 v167, v89
	v_fmamk_f32 v222, v75, 0x3e0293ee, v213
	v_fmamk_f32 v223, v64, 0x3e0293ee, v213
	v_fmamk_f32 v224, v65, 0x3e0293ee, v213
	v_fmamk_f32 v225, v66, 0x3e0293ee, v213
	v_mfma_f32_32x32x16_bf16 v[16:31], v[174:177], v[226:229], v[16:31]
	v_exp_f32_e32 v168, v92
	v_fmamk_f32 v226, v67, 0x3e0293ee, v213
	v_fmamk_f32 v227, v68, 0x3e0293ee, v213
	v_fmamk_f32 v228, v77, 0x3e0293ee, v213
	v_fmamk_f32 v229, v78, 0x3e0293ee, v213
	v_fmac_f32_e32 v213, 0x3e0293ee, v79
	s_barrier
	s_waitcnt vmcnt(4)
	v_cndmask_b32_e64 v214, v233, 1.0, s[8:9]
	v_cmp_gt_f32_e32 vcc, 1.0, v214
	s_waitcnt vmcnt(7)
	ds_write_b128 v204, v[98:101]
	s_waitcnt vmcnt(6)
	ds_write_b128 v205, v[138:141]
	s_cbranch_vccz .LBB0_606
	s_and_saveexec_b64 s[12:13], s[6:7]
	ds_write_b32 v189, v214 offset:128
	s_or_b64 exec, exec, s[12:13]
	s_waitcnt lgkmcnt(0)
	v_add_u32_e32 v232, v181, v180
	ds_read_b128 v[98:101], v232 offset:224
	ds_read_b128 v[138:141], v232 offset:192
	ds_read_b128 v[102:105], v232 offset:160
	ds_read_b128 v[142:145], v232 offset:128
	s_waitcnt lgkmcnt(3)
	v_pk_mul_f32 v[12:13], v[12:13], v[98:99]
	s_waitcnt lgkmcnt(2)
	v_pk_mul_f32 v[8:9], v[8:9], v[138:139]
	s_waitcnt lgkmcnt(1)
	v_pk_mul_f32 v[4:5], v[4:5], v[102:103]
	v_pk_mul_f32 v[14:15], v[14:15], v[100:101]
	v_pk_mul_f32 v[10:11], v[10:11], v[140:141]
	v_pk_mul_f32 v[6:7], v[6:7], v[104:105]
	s_waitcnt lgkmcnt(0)
	v_pk_mul_f32 v[2:3], v[2:3], v[144:145]
	v_pk_mul_f32 v[0:1], v[0:1], v[142:143]
	v_pk_mul_f32 v[60:61], v[60:61], v[98:99]
	v_pk_mul_f32 v[56:57], v[56:57], v[138:139]
	v_pk_mul_f32 v[52:53], v[52:53], v[102:103]
	v_pk_mul_f32 v[62:63], v[62:63], v[100:101]
	v_pk_mul_f32 v[58:59], v[58:59], v[140:141]
	v_pk_mul_f32 v[54:55], v[54:55], v[104:105]
	v_pk_mul_f32 v[50:51], v[50:51], v[144:145]
	v_pk_mul_f32 v[48:49], v[48:49], v[142:143]
	v_pk_mul_f32 v[44:45], v[44:45], v[98:99]
	v_pk_mul_f32 v[40:41], v[40:41], v[138:139]
	v_pk_mul_f32 v[36:37], v[36:37], v[102:103]
	v_pk_mul_f32 v[46:47], v[46:47], v[100:101]
	v_pk_mul_f32 v[42:43], v[42:43], v[140:141]
	v_pk_mul_f32 v[38:39], v[38:39], v[104:105]
	v_pk_mul_f32 v[34:35], v[34:35], v[144:145]
	v_pk_mul_f32 v[32:33], v[32:33], v[142:143]
	v_pk_mul_f32 v[28:29], v[28:29], v[98:99]
	v_pk_mul_f32 v[24:25], v[24:25], v[138:139]
	v_pk_mul_f32 v[20:21], v[20:21], v[102:103]
	v_pk_mul_f32 v[30:31], v[30:31], v[100:101]
	v_pk_mul_f32 v[26:27], v[26:27], v[140:141]
	v_pk_mul_f32 v[22:23], v[22:23], v[104:105]
	v_pk_mul_f32 v[18:19], v[18:19], v[144:145]
	v_pk_mul_f32 v[16:17], v[16:17], v[142:143]
; __device__ __forceinline__ void finishSM(f32x16& p0, f32x16& p1, float alpha, float& l_reg, bf16x8& pa0, bf16x8& pa1, bf16x8& pa2, bf16x8& pa3) {
;   for (int r = 0; r < 16; ++r) p1[r] = __builtin_amdgcn_exp2f(p1[r]);
;   float ps = 0; for (int r = 0; r < 16; ++r) ps += p0[r]; for (int r = 0; r < 16; ++r) ps += p1[r];
;   { auto rr = __builtin_amdgcn_permlane32_swap(__float_as_uint(ps), __float_as_uint(ps), false, false);
;     ps = __uint_as_float(rr[0]) + __uint_as_float(rr[1]); }
;   l_reg = l_reg * alpha + ps;
;     ...
;   PK4(p0, 0, pa0); PK4(p0, 8, pa1); PK4(p1, 0, pa2); PK4(p1, 8, pa3);
;     ...
; }
; __device__ __forceinline__ void qkt(f32x16& p0, f32x16& p1, const bf16* Ks, const bf16x8* qr, int r32, int hi) {
;   p0 = f32x16{}; p1 = f32x16{};
;   for (int d0 = 0; d0 < 8; ++d0) { int cb = (d0 * 16 + hi * 8) * 2;
;     bf16x8 b0 = *reinterpret_cast<const bf16x8*>((const char*)Ks + KSWZ(r32, cb));
;     bf16x8 b1 = *reinterpret_cast<const bf16x8*>((const char*)Ks + KSWZ(32 + r32, cb));
;     p0 = __builtin_amdgcn_mfma_f32_32x32x16_bf16(b0, qr[d0], p0, 0, 0, 0);
;     p1 = __builtin_amdgcn_mfma_f32_32x32x16_bf16(b1, qr[d0], p1, 0, 0, 0); }
.LBB0_606:
	v_mov_b32_e32 v175, v83
	v_mov_b32_e32 v176, v84
	v_mov_b32_e32 v177, v85
	v_mov_b32_e32 v174, v87
	v_mov_b32_e32 v172, v90
	v_mov_b32_e32 v173, v91
	v_mov_b32_e32 v169, v93
	v_mov_b32_e32 v170, v94
	v_mov_b32_e32 v171, v95
	ds_read_b128 v[64:67], v192 offset:32768
	ds_read_b128 v[68:71], v192 offset:40960
	ds_read_b128 v[242:245], v201 offset:32768
	ds_read_b128 v[246:249], v201 offset:40960
	v_add_f32_e32 v230, 0, v162
	v_add_f32_e32 v230, v163, v230
	s_waitcnt lgkmcnt(3)
	v_mfma_f32_32x32x16_bf16 v[80:95], v[64:67], v[126:129], 0
	v_add_f32_e32 v230, v164, v230
	v_add_f32_e32 v230, v175, v230
	v_add_f32_e32 v230, v176, v230
	v_add_f32_e32 v230, v177, v230
	v_add_f32_e32 v230, v165, v230
	v_add_f32_e32 v230, v174, v230
	v_add_f32_e32 v230, v166, v230
	s_waitcnt lgkmcnt(2)
	v_mfma_f32_32x32x16_bf16 v[64:79], v[68:71], v[126:129], 0
	v_add_f32_e32 v230, v167, v230
	v_add_f32_e32 v230, v172, v230
	v_add_f32_e32 v230, v173, v230
	v_exp_f32_e32 v223, v223
	v_add_f32_e32 v230, v168, v230
	v_exp_f32_e32 v224, v224
	v_add_f32_e32 v230, v169, v230
	s_waitcnt lgkmcnt(1)
	v_mfma_f32_32x32x16_bf16 v[80:95], v[242:245], v[122:125], v[80:95]
	v_exp_f32_e32 v225, v225
	v_add_f32_e32 v230, v170, v230
	v_exp_f32_e32 v226, v226
	v_add_f32_e32 v230, v171, v230
	v_exp_f32_e32 v227, v227
	v_add_f32_e32 v230, v223, v230
	v_exp_f32_e32 v216, v216
	s_waitcnt lgkmcnt(0)
	v_mfma_f32_32x32x16_bf16 v[64:79], v[246:249], v[122:125], v[64:79]
	ds_read_b128 v[242:245], v200 offset:32768
	ds_read_b128 v[246:249], v200 offset:40960
	v_add_f32_e32 v230, v224, v230
	v_exp_f32_e32 v217, v217
	v_add_f32_e32 v230, v225, v230
	v_exp_f32_e32 v218, v218
	v_add_f32_e32 v230, v226, v230
	v_exp_f32_e32 v219, v219
	s_waitcnt lgkmcnt(1)
	v_mfma_f32_32x32x16_bf16 v[80:95], v[242:245], v[134:137], v[80:95]
	v_add_f32_e32 v230, v227, v230
	v_exp_f32_e32 v220, v220
	v_add_f32_e32 v230, v216, v230
	v_exp_f32_e32 v221, v221
	v_add_f32_e32 v230, v217, v230
	v_exp_f32_e32 v222, v222
	v_add_f32_e32 v230, v218, v230
	s_waitcnt lgkmcnt(0)
	v_mfma_f32_32x32x16_bf16 v[64:79], v[246:249], v[134:137], v[64:79]
	ds_read_b128 v[242:245], v195 offset:32768
	ds_read_b128 v[246:249], v195 offset:40960
	v_exp_f32_e32 v215, v215
	v_add_f32_e32 v230, v219, v230
	v_exp_f32_e32 v228, v228
	v_add_f32_e32 v230, v220, v230
	v_exp_f32_e32 v229, v229
	v_add_f32_e32 v230, v221, v230
	s_waitcnt lgkmcnt(1)
	v_mfma_f32_32x32x16_bf16 v[80:95], v[242:245], v[130:133], v[80:95]
	v_exp_f32_e32 v213, v213
	v_add_f32_e32 v230, v222, v230
	v_add_f32_e32 v230, v215, v230
	v_add_f32_e32 v230, v228, v230
	v_add_f32_e32 v230, v229, v230
	v_add_f32_e32 v231, v213, v230
	v_mov_b32_e32 v241, v231
	s_waitcnt lgkmcnt(0)
	v_mfma_f32_32x32x16_bf16 v[64:79], v[246:249], v[130:133], v[64:79]
	ds_read_b128 v[242:245], v194 offset:32768
	ds_read_b128 v[246:249], v194 offset:40960
	v_cvt_pk_bf16_f32 v162, v162, v163
	v_cvt_pk_bf16_f32 v163, v164, v175
	v_cvt_pk_bf16_f32 v164, v176, v177
	v_cvt_pk_bf16_f32 v165, v165, v174
	v_cvt_pk_bf16_f32 v166, v166, v167
	v_cvt_pk_bf16_f32 v167, v172, v173
	s_waitcnt lgkmcnt(1)
	v_mfma_f32_32x32x16_bf16 v[80:95], v[242:245], v[118:121], v[80:95]
	v_cvt_pk_bf16_f32 v168, v168, v169
	v_cvt_pk_bf16_f32 v169, v170, v171
	v_cvt_pk_bf16_f32 v170, v223, v224
	v_cvt_pk_bf16_f32 v171, v225, v226
	v_cvt_pk_bf16_f32 v172, v227, v216
	v_cvt_pk_bf16_f32 v173, v217, v218
	v_cvt_pk_bf16_f32 v174, v219, v220
	s_waitcnt lgkmcnt(0)
	v_mfma_f32_32x32x16_bf16 v[64:79], v[246:249], v[118:121], v[64:79]
	ds_read_b128 v[242:245], v193 offset:32768
	ds_read_b128 v[246:249], v193 offset:40960
	v_cvt_pk_bf16_f32 v175, v221, v222
	v_cvt_pk_bf16_f32 v176, v215, v228
	v_cvt_pk_bf16_f32 v177, v229, v213
	v_permlane32_swap_b32_e32 v231, v241
	v_permlane32_swap_b32_e32 v162, v164
	s_waitcnt lgkmcnt(1)
	v_mfma_f32_32x32x16_bf16 v[80:95], v[242:245], v[114:117], v[80:95]
	v_permlane32_swap_b32_e32 v163, v165
	v_permlane32_swap_b32_e32 v166, v168
	v_permlane32_swap_b32_e32 v167, v169
	v_permlane32_swap_b32_e32 v170, v172
	s_waitcnt lgkmcnt(0)
	v_mfma_f32_32x32x16_bf16 v[64:79], v[246:249], v[114:117], v[64:79]
	ds_read_b128 v[242:245], v207 offset:32768
	ds_read_b128 v[246:249], v207 offset:40960
	v_permlane32_swap_b32_e32 v171, v173
	v_permlane32_swap_b32_e32 v174, v176
	v_permlane32_swap_b32_e32 v175, v177
	s_waitcnt lgkmcnt(1)
	v_mfma_f32_32x32x16_bf16 v[80:95], v[242:245], v[110:113], v[80:95]
	s_waitcnt lgkmcnt(0)
	v_mfma_f32_32x32x16_bf16 v[64:79], v[246:249], v[110:113], v[64:79]
	ds_read_b128 v[242:245], v206 offset:32768
	ds_read_b128 v[246:249], v206 offset:40960
	s_waitcnt lgkmcnt(1)
	v_mfma_f32_32x32x16_bf16 v[80:95], v[242:245], v[106:109], v[80:95]
	s_waitcnt lgkmcnt(0)
	v_mfma_f32_32x32x16_bf16 v[64:79], v[246:249], v[106:109], v[64:79]
	s_cmp_ge_u32 s40, s41
	s_cselect_b64 s[12:13], -1, 0
	s_and_b64 vcc, exec, s[12:13]
	s_cbranch_vccnz .LBB0_608
	v_add_co_u32_e32 v98, vcc, 0xffff8000, v182
	s_nop 1
	v_addc_co_u32_e32 v99, vcc, -1, v183, vcc
	v_add_co_u32_e32 v102, vcc, 0xff6f8000, v182
	s_nop 1
	v_addc_co_u32_e32 v103, vcc, -1, v183, vcc
	v_add_co_u32_e32 v142, vcc, 0xff700000, v182
	global_load_dwordx4 v[98:101], v[98:99], off
	s_nop 0
	global_load_dwordx4 v[102:105], v[102:103], off
	v_addc_co_u32_e32 v143, vcc, -1, v183, vcc
	global_load_dwordx4 v[138:141], v[182:183], off
	s_nop 0
	global_load_dwordx4 v[142:145], v[142:143], off

; #define SBAR() __builtin_amdgcn_sched_barrier(0)
; __device__ __forceinline__ void partialSM(f32x16& p0, f32x16& p1, float& m_reg, float& mn, float& alpha) {
;   constexpr float C = SCALE * 1.4426950408889634f;
;   float pmax = p0[0]; for (int r = 1; r < 16; ++r) pmax = fmaxf(pmax, p0[r]); for (int r = 0; r < 16; ++r) pmax = fmaxf(pmax, p1[r]);
;   { auto rr = __builtin_amdgcn_permlane32_swap(__float_as_uint(pmax), __float_as_uint(pmax), false, false);
;     pmax = fmaxf(__uint_as_float(rr[0]), __uint_as_float(rr[1])); }
;   if (__builtin_expect(__all(pmax - m_reg <= THR / SCALE), 1)) { mn = m_reg; alpha = 1.f; }
;   else { mn = fmaxf(m_reg, pmax); alpha = __builtin_amdgcn_exp2f((m_reg - mn) * C); m_reg = mn; }
;   float mnC = -mn * C;
;   for (int r = 0; r < 16; ++r) p0[r] = fmaf(p0[r], C, mnC); for (int r = 0; r < 16; ++r) p1[r] = fmaf(p1[r], C, mnC);
;   for (int r = 0; r < 16; ++r) p0[r] = __builtin_amdgcn_exp2f(p0[r]);
; template <int D0> __device__ __forceinline__ void pv_one(f32x16& od, int vb, bf16x8 pa0, bf16x8 pa1, bf16x8 pa2, bf16x8 pa3) {
;   const s16x4 l0 = tr_read<v_rd_off(D0, 0, 0)>(vb), h0 = tr_read<v_rd_off(D0, 0, 1)>(vb), l1 = tr_read<v_rd_off(D0, 1, 0)>(vb), h1 = tr_read<v_rd_off(D0, 1, 1)>(vb);
;   const s16x4 l2 = tr_read<v_rd_off(D0, 2, 0)>(vb), h2 = tr_read<v_rd_off(D0, 2, 1)>(vb), l3 = tr_read<v_rd_off(D0, 3, 0)>(vb), h3 = tr_read<v_rd_off(D0, 3, 1)>(vb);
;   asm volatile("s_waitcnt lgkmcnt(0)" ::: "memory"); SBAR();
;     ...
;   od = __builtin_amdgcn_mfma_f32_32x32x16_bf16(pa0, PK(l0, h0), od, 0, 0, 0);
;   od = __builtin_amdgcn_mfma_f32_32x32x16_bf16(pa1, PK(l1, h1), od, 0, 0, 0);
;   od = __builtin_amdgcn_mfma_f32_32x32x16_bf16(pa2, PK(l2, h2), od, 0, 0, 0);
;   od = __builtin_amdgcn_mfma_f32_32x32x16_bf16(pa3, PK(l3, h3), od, 0, 0, 0);
;     ...
; }
; __device__ __forceinline__ void pv_d0(f32x16* o, int vb, bf16x8 pa0, bf16x8 pa1, bf16x8 pa2, bf16x8 pa3) {
;   pv_one<0>(o[0], vb, pa0, pa1, pa2, pa3); pv_one<1>(o[1], vb, pa0, pa1, pa2, pa3); pv_one<2>(o[2], vb, pa0, pa1, pa2, pa3); pv_one<3>(o[3], vb, pa0, pa1, pa2, pa3);
.Lk_wd:
	ds_write_b128 v202, v[154:157] offset:49152
	ds_write_b128 v203, v[158:161] offset:49152
	s_waitcnt lgkmcnt(2)
	s_nop 0
	v_mfma_f32_32x32x16_bf16 v[0:15], v[162:165], v[216:219], v[0:15]
	ds_read_b64_tr_b16 v[216:217], v191 offset:0x200
	ds_read_b64_tr_b16 v[218:219], v191 offset:0xa00
	v_max_f32_e32 v232, v81, v81
	v_max_f32_e32 v233, v80, v80
	v_max_f32_e32 v232, v233, v232
	v_max3_f32 v232, v232, v82, v83
	v_max3_f32 v232, v232, v84, v85
	v_max3_f32 v232, v232, v86, v87
	v_mfma_f32_32x32x16_bf16 v[0:15], v[166:169], v[220:223], v[0:15]
	ds_read_b64_tr_b16 v[220:221], v191 offset:0x1200
	ds_read_b64_tr_b16 v[222:223], v191 offset:0x1a00
	v_max3_f32 v232, v232, v88, v89
	v_max3_f32 v232, v232, v90, v91
	v_max3_f32 v232, v232, v92, v93
	v_max3_f32 v232, v232, v94, v95
	v_max3_f32 v232, v232, v64, v65
	v_max3_f32 v232, v232, v66, v67
	v_mfma_f32_32x32x16_bf16 v[0:15], v[170:173], v[224:227], v[0:15]
	ds_read_b64_tr_b16 v[224:225], v191 offset:0x2200
	ds_read_b64_tr_b16 v[226:227], v191 offset:0x2a00
	v_max3_f32 v232, v232, v68, v69
	v_max3_f32 v232, v232, v70, v71
	v_max3_f32 v232, v232, v72, v73
	v_max3_f32 v232, v232, v74, v75
	v_max3_f32 v232, v232, v76, v77
	v_max3_f32 v232, v232, v78, v79
	v_mfma_f32_32x32x16_bf16 v[0:15], v[174:177], v[242:245], v[0:15]
	ds_read_b64_tr_b16 v[242:243], v191 offset:0x3200
	ds_read_b64_tr_b16 v[244:245], v191 offset:0x3a00
	v_mov_b32_e32 v233, v232
	s_nop 1
	v_permlane32_swap_b32_e32 v232, v233
	v_max_f32_e32 v233, v233, v233
	v_max_f32_e32 v232, v232, v232
	v_max_f32_e32 v232, v232, v233
	s_waitcnt lgkmcnt(0)
	v_mfma_f32_32x32x16_bf16 v[48:63], v[162:165], v[216:219], v[48:63]
	ds_read_b64_tr_b16 v[216:217], v191 offset:0x400
	ds_read_b64_tr_b16 v[218:219], v191 offset:0xc00
	v_sub_f32_e32 v233, v232, v210
	v_cmp_ge_f32_e32 vcc, s68, v233
	v_max_f32_e32 v233, v210, v210
	v_max_f32_e32 v232, v233, v232
	v_sub_f32_e32 v233, v210, v232
	v_mul_f32_e32 v233, 0x3e0293ee, v233
	v_mfma_f32_32x32x16_bf16 v[48:63], v[166:169], v[220:223], v[48:63]
	ds_read_b64_tr_b16 v[220:221], v191 offset:0x1400
	ds_read_b64_tr_b16 v[222:223], v191 offset:0x1c00
	s_cmp_eq_u64 vcc, exec
	s_cselect_b64 s[8:9], -1, 0
	v_exp_f32_e32 v233, v233
	v_mfma_f32_32x32x16_bf16 v[48:63], v[170:173], v[224:227], v[48:63]
	ds_read_b64_tr_b16 v[224:225], v191 offset:0x2400
	ds_read_b64_tr_b16 v[226:227], v191 offset:0x2c00
	v_cndmask_b32_e64 v210, v232, v210, s[8:9]
	v_mul_f32_e32 v250, 0xbe0293ee, v210
	v_fmamk_f32 v84, v84, 0x3e0293ee, v250
	v_fmamk_f32 v85, v85, 0x3e0293ee, v250
	v_fmamk_f32 v87, v87, 0x3e0293ee, v250
	v_fmamk_f32 v88, v88, 0x3e0293ee, v250
	v_mfma_f32_32x32x16_bf16 v[48:63], v[174:177], v[242:245], v[48:63]
	ds_read_b64_tr_b16 v[242:243], v191 offset:0x3400
	ds_read_b64_tr_b16 v[244:245], v191 offset:0x3c00
	v_fmamk_f32 v80, v80, 0x3e0293ee, v250
	v_fmamk_f32 v81, v81, 0x3e0293ee, v250
	v_fmamk_f32 v82, v82, 0x3e0293ee, v250
	v_fmamk_f32 v83, v83, 0x3e0293ee, v250
	v_exp_f32_e32 v229, v84
	s_waitcnt lgkmcnt(0)
	v_mfma_f32_32x32x16_bf16 v[32:47], v[162:165], v[216:219], v[32:47]
	ds_read_b64_tr_b16 v[216:217], v191 offset:0x600
	ds_read_b64_tr_b16 v[218:219], v191 offset:0xe00
	v_fmamk_f32 v86, v86, 0x3e0293ee, v250
	v_fmamk_f32 v89, v89, 0x3e0293ee, v250
	v_fmamk_f32 v90, v90, 0x3e0293ee, v250
	v_fmamk_f32 v91, v91, 0x3e0293ee, v250
	v_exp_f32_e32 v230, v85
	v_mfma_f32_32x32x16_bf16 v[32:47], v[166:169], v[220:223], v[32:47]
	ds_read_b64_tr_b16 v[220:221], v191 offset:0x1600
	ds_read_b64_tr_b16 v[222:223], v191 offset:0x1e00
	v_fmamk_f32 v92, v92, 0x3e0293ee, v250
	v_fmamk_f32 v93, v93, 0x3e0293ee, v250
	v_fmamk_f32 v94, v94, 0x3e0293ee, v250
	v_fmamk_f32 v95, v95, 0x3e0293ee, v250
	v_exp_f32_e32 v228, v87
	v_mfma_f32_32x32x16_bf16 v[32:47], v[170:173], v[224:227], v[32:47]
	ds_read_b64_tr_b16 v[224:225], v191 offset:0x2600
	ds_read_b64_tr_b16 v[226:227], v191 offset:0x2e00
	v_exp_f32_e32 v215, v88
	v_exp_f32_e32 v80, v80
	v_exp_f32_e32 v81, v81
	v_mfma_f32_32x32x16_bf16 v[32:47], v[174:177], v[242:245], v[32:47]
	ds_read_b64_tr_b16 v[242:243], v191 offset:0x3600
	ds_read_b64_tr_b16 v[244:245], v191 offset:0x3e00
	v_exp_f32_e32 v82, v82
	v_exp_f32_e32 v83, v83
	v_exp_f32_e32 v86, v86
	s_waitcnt lgkmcnt(0)
	v_mfma_f32_32x32x16_bf16 v[16:31], v[162:165], v[216:219], v[16:31]
	v_exp_f32_e32 v216, v92
	v_exp_f32_e32 v217, v89
	v_pk_fma_f32 v[164:165], v[72:73], s[84:85], v[250:251] op_sel_hi:[1,0,0]
	v_pk_fma_f32 v[162:163], v[78:79], s[84:85], v[250:251] op_sel_hi:[1,0,0]
	v_mfma_f32_32x32x16_bf16 v[16:31], v[166:169], v[220:223], v[16:31]
	v_exp_f32_e32 v218, v93
	v_exp_f32_e32 v219, v90
	v_pk_fma_f32 v[166:167], v[70:71], s[84:85], v[250:251] op_sel_hi:[1,0,0]
	v_pk_fma_f32 v[168:169], v[76:77], s[84:85], v[250:251] op_sel_hi:[1,0,0]
	v_mfma_f32_32x32x16_bf16 v[16:31], v[170:173], v[224:227], v[16:31]
	v_exp_f32_e32 v220, v94
	v_exp_f32_e32 v221, v91
	v_pk_fma_f32 v[170:171], v[68:69], s[84:85], v[250:251] op_sel_hi:[1,0,0]
	v_pk_fma_f32 v[172:173], v[74:75], s[84:85], v[250:251] op_sel_hi:[1,0,0]
	v_mfma_f32_32x32x16_bf16 v[16:31], v[174:177], v[242:245], v[16:31]
	v_exp_f32_e32 v222, v95
	v_pk_fma_f32 v[174:175], v[66:67], s[84:85], v[250:251] op_sel_hi:[1,0,0]
	v_pk_fma_f32 v[176:177], v[64:65], s[84:85], v[250:251] op_sel_hi:[1,0,0]
	s_barrier
; __device__ __forceinline__ void finishSM(f32x16& p0, f32x16& p1, float alpha, float& l_reg, bf16x8& pa0, bf16x8& pa1, bf16x8& pa2, bf16x8& pa3) {
;     ...
;   { auto rr = __builtin_amdgcn_permlane32_swap(__float_as_uint(ps), __float_as_uint(ps), false, false);
;     ps = __uint_as_float(rr[0]) + __uint_as_float(rr[1]); }
;   l_reg = l_reg * alpha + ps;
	s_waitcnt vmcnt(4)
	v_cndmask_b32_e64 v213, v233, 1.0, s[8:9]
	v_cmp_gt_f32_e32 vcc, 1.0, v213
	ds_write_b128 v204, v[146:149] offset:16384
	ds_write_b128 v205, v[150:153] offset:16384
	s_cbranch_vccz .LBB0_612
	s_and_saveexec_b64 s[18:19], s[6:7]
	ds_write_b32 v189, v213 offset:128
	s_or_b64 exec, exec, s[18:19]
	s_waitcnt lgkmcnt(0)
	v_add_u32_e32 v158, v181, v180
	ds_read_b128 v[146:149], v158 offset:224
	ds_read_b128 v[150:153], v158 offset:192
	ds_read_b128 v[154:157], v158 offset:160
	ds_read_b128 v[158:161], v158 offset:128
	s_waitcnt lgkmcnt(3)
	v_pk_mul_f32 v[12:13], v[12:13], v[146:147]
	s_waitcnt lgkmcnt(2)
	v_pk_mul_f32 v[8:9], v[8:9], v[150:151]
	s_waitcnt lgkmcnt(1)
	v_pk_mul_f32 v[4:5], v[4:5], v[154:155]
	v_pk_mul_f32 v[14:15], v[14:15], v[148:149]
	v_pk_mul_f32 v[10:11], v[10:11], v[152:153]
	v_pk_mul_f32 v[6:7], v[6:7], v[156:157]
	s_waitcnt lgkmcnt(0)
	v_pk_mul_f32 v[2:3], v[2:3], v[160:161]
	v_pk_mul_f32 v[0:1], v[0:1], v[158:159]
	v_pk_mul_f32 v[60:61], v[60:61], v[146:147]
	v_pk_mul_f32 v[56:57], v[56:57], v[150:151]
	v_pk_mul_f32 v[52:53], v[52:53], v[154:155]
	v_pk_mul_f32 v[62:63], v[62:63], v[148:149]
	v_pk_mul_f32 v[58:59], v[58:59], v[152:153]
	v_pk_mul_f32 v[54:55], v[54:55], v[156:157]
	v_pk_mul_f32 v[50:51], v[50:51], v[160:161]
	v_pk_mul_f32 v[48:49], v[48:49], v[158:159]
	v_pk_mul_f32 v[44:45], v[44:45], v[146:147]
	v_pk_mul_f32 v[40:41], v[40:41], v[150:151]
	v_pk_mul_f32 v[36:37], v[36:37], v[154:155]
	v_pk_mul_f32 v[46:47], v[46:47], v[148:149]
	v_pk_mul_f32 v[42:43], v[42:43], v[152:153]
	v_pk_mul_f32 v[38:39], v[38:39], v[156:157]
	v_pk_mul_f32 v[34:35], v[34:35], v[160:161]
	v_pk_mul_f32 v[32:33], v[32:33], v[158:159]
	v_pk_mul_f32 v[28:29], v[28:29], v[146:147]
	v_pk_mul_f32 v[24:25], v[24:25], v[150:151]
	v_pk_mul_f32 v[20:21], v[20:21], v[154:155]
	v_pk_mul_f32 v[30:31], v[30:31], v[148:149]
	v_pk_mul_f32 v[26:27], v[26:27], v[152:153]
	v_pk_mul_f32 v[22:23], v[22:23], v[156:157]
	v_pk_mul_f32 v[18:19], v[18:19], v[160:161]
	v_pk_mul_f32 v[16:17], v[16:17], v[158:159]
.LBB0_612:
	v_mov_b32_e32 v223, v80
	v_mov_b32_e32 v224, v81
	v_mov_b32_e32 v225, v82
	v_mov_b32_e32 v227, v83
	v_mov_b32_e32 v226, v86
	v_add_f32_e32 v64, v211, v212
	v_fmac_f32_e32 v64, v209, v190
	v_add_f32_e32 v190, v231, v241
	v_fmac_f32_e32 v190, v64, v214
	s_add_i32 s40, s40, 2
	v_lshl_add_u64 v[182:183], v[182:183], 0, s[82:83]
	s_and_b64 vcc, exec, s[12:13]
	s_cbranch_vccnz .LBB0_614
	v_mov_b32_e32 v209, v213
	s_branch .LBB0_602
